# v58 plus mirrored row-block assignment for waves 4-7 in ssd_passC and gla_passC causal loops (balances tile iterations across SIMDs)
# speedup vs baseline: 1.0105x; 1.0105x over previous
.LBB0_165:
	s_cmpk_lt_u32 s85, 0x400
	s_cbranch_scc1 .LBB0_173
	s_add_i32 s2, s85, 0xfffffc00
	s_lshl_b32 s42, s2, 2
	s_lshl_b32 s7, s2, 6
	s_mov_b32 s2, 7
	s_ashr_i32 s3, s2, 31
	s_lshl_b64 s[2:3], s[2:3], 3
	s_add_u32 s2, s0, s2
	s_addc_u32 s3, s1, s3
	s_load_dwordx2 s[2:3], s[2:3], 0x0
	s_mov_b32 s10, 8
	v_mov_b32_e32 v109, v183
	v_mov_b32_e32 v66, v1
	s_waitcnt lgkmcnt(0)
	s_add_u32 s40, s2, s92
	s_addc_u32 s41, s3, s93
	s_ashr_i32 s11, s10, 31
	s_lshl_b64 s[2:3], s[10:11], 3
	s_add_u32 s2, s0, s2
	s_addc_u32 s3, s1, s3
	s_load_dwordx2 s[2:3], s[2:3], 0x0
	s_lshl_b64 s[68:69], s[34:35], 2
	s_mov_b32 s10, 9
	v_mov_b32_e32 v83, v1
	s_waitcnt lgkmcnt(0)
	s_add_u32 s38, s2, s68
	s_addc_u32 s39, s3, s69
	s_ashr_i32 s11, s10, 31
	s_lshl_b64 s[2:3], s[10:11], 3
	s_add_u32 s2, s0, s2
	s_addc_u32 s3, s1, s3
	s_load_dwordx2 s[20:21], s[2:3], 0x0
	v_readlane_b32 s2, v254, 56
	s_waitcnt lgkmcnt(0)
	v_readfirstlane_b32 s11, v109
	s_bitcmp1_b32 s11, 8
	s_cselect_b32 s3, 64, 0
	s_xor_b32 s11, s11, s3
	v_mov_b32_e32 v85, s2
	v_readlane_b32 s2, v254, 57
	s_ashr_i32 s10, s11, 7
	s_ashr_i32 s6, s11, 6
	v_mov_b32_e32 v87, s2
	s_add_i32 s2, 0, 0x1b000
	v_mov_b32_e32 v189, s2
	v_readlane_b32 s2, v254, 58
	v_lshrrev_b32_e32 v0, 1, v109
	v_and_b32_e32 v0, 16, v0
	v_mov_b32_e32 v187, s2
	s_add_i32 s2, s10, s42
	s_ashr_i32 s3, s2, 31
	s_lshl_b64 s[2:3], s[2:3], 13
	v_readlane_b32 s42, v254, 3
	v_readlane_b32 s43, v254, 4
	s_add_u32 s2, s42, s2
	s_addc_u32 s3, s43, s3
	v_lshl_add_u64 v[2:3], s[2:3], 0, v[0:1]
	v_lshlrev_b32_e32 v0, 7, v109
	v_and_b32_e32 v0, 0xf80, v0
	v_and_b32_e32 v84, 63, v109
	v_lshl_add_u64 v[4:5], v[2:3], 0, v[0:1]
	v_mov_b32_e32 v0, 0x1000
	v_lshl_or_b32 v0, v84, 7, v0
	v_lshl_add_u64 v[2:3], v[2:3], 0, v[0:1]
	v_ashrrev_i32_e32 v160, 8, v109
	s_barrier
	global_load_dwordx4 v[62:65], v[4:5], off
	global_load_dwordx4 v[58:61], v[4:5], off offset:32
	global_load_dwordx4 v[54:57], v[4:5], off offset:64
	global_load_dwordx4 v[50:53], v[4:5], off offset:96
	global_load_dwordx4 v[46:49], v[2:3], off
	global_load_dwordx4 v[42:45], v[2:3], off offset:32
	global_load_dwordx4 v[38:41], v[2:3], off offset:64
	global_load_dwordx4 v[34:37], v[2:3], off offset:96
	v_lshl_add_u32 v30, v160, 5, s7
	v_mov_b64_e32 v[2:3], s[26:27]
	v_mad_i64_i32 v[4:5], s[2:3], v30, s18, v[2:3]
	v_lshlrev_b32_sdwa v0, v180, v109 dst_sel:DWORD dst_unused:UNUSED_PAD src0_sel:DWORD src1_sel:BYTE_0
	v_or_b32_e32 v6, 1, v30
	v_or_b32_e32 v8, 2, v30
	v_lshl_add_u64 v[4:5], v[4:5], 0, v[0:1]
	v_mad_i64_i32 v[6:7], s[2:3], v6, s18, v[2:3]
	v_mad_i64_i32 v[8:9], s[2:3], v8, s18, v[2:3]
	v_lshl_add_u64 v[6:7], v[6:7], 0, v[0:1]
	v_lshl_add_u64 v[8:9], v[8:9], 0, v[0:1]
	flat_load_ushort v185, v[4:5]
	flat_load_ushort v169, v[4:5] offset:512
	flat_load_ushort v168, v[4:5] offset:1024
	flat_load_ushort v161, v[6:7]
	s_nop 0
	flat_load_ushort v156, v[6:7] offset:512
	flat_load_ushort v155, v[6:7] offset:1024
	flat_load_ushort v148, v[8:9]
	flat_load_ushort v144, v[8:9] offset:512
	v_or_b32_e32 v4, 3, v30
	v_mad_i64_i32 v[4:5], s[2:3], v4, s18, v[2:3]
	v_or_b32_e32 v6, 4, v30
	v_or_b32_e32 v10, 5, v30
	v_lshl_add_u64 v[4:5], v[4:5], 0, v[0:1]
	v_mad_i64_i32 v[6:7], s[2:3], v6, s18, v[2:3]
	v_mad_i64_i32 v[10:11], s[2:3], v10, s18, v[2:3]
	v_lshl_add_u64 v[6:7], v[6:7], 0, v[0:1]
	v_lshl_add_u64 v[10:11], v[10:11], 0, v[0:1]
	flat_load_ushort v163, v[8:9] offset:1024
	flat_load_ushort v152, v[4:5]
	flat_load_ushort v151, v[4:5] offset:512
	flat_load_ushort v150, v[4:5] offset:1024
	flat_load_ushort v141, v[6:7]
	flat_load_ushort v139, v[6:7] offset:512
	flat_load_ushort v137, v[6:7] offset:1024
	flat_load_ushort v132, v[10:11]
	v_or_b32_e32 v4, 6, v30
	v_mad_i64_i32 v[4:5], s[2:3], v4, s18, v[2:3]
	v_or_b32_e32 v6, 7, v30
	v_lshl_add_u64 v[4:5], v[4:5], 0, v[0:1]
	v_mad_i64_i32 v[6:7], s[2:3], v6, s18, v[2:3]
	v_lshl_add_u64 v[6:7], v[6:7], 0, v[0:1]
	flat_load_ushort v140, v[10:11] offset:512
	flat_load_ushort v138, v[10:11] offset:1024
	flat_load_ushort v133, v[4:5]
	flat_load_ushort v131, v[4:5] offset:512
	flat_load_ushort v130, v[4:5] offset:1024
	flat_load_ushort v126, v[6:7]
	flat_load_ushort v124, v[6:7] offset:512
	flat_load_ushort v123, v[6:7] offset:1024
	v_or_b32_e32 v4, 8, v30
	v_mad_i64_i32 v[4:5], s[2:3], v4, s18, v[2:3]
	v_or_b32_e32 v6, 9, v30
	v_or_b32_e32 v8, 10, v30
	v_lshl_add_u64 v[4:5], v[4:5], 0, v[0:1]
	v_mad_i64_i32 v[6:7], s[2:3], v6, s18, v[2:3]
	v_mad_i64_i32 v[8:9], s[2:3], v8, s18, v[2:3]
	v_lshl_add_u64 v[6:7], v[6:7], 0, v[0:1]
	v_lshl_add_u64 v[8:9], v[8:9], 0, v[0:1]
	flat_load_ushort v122, v[4:5]
	flat_load_ushort v120, v[4:5] offset:512
	flat_load_ushort v119, v[4:5] offset:1024
	flat_load_ushort v113, v[6:7]
	flat_load_ushort v112, v[6:7] offset:512
	flat_load_ushort v111, v[6:7] offset:1024
	flat_load_ushort v101, v[8:9]
	flat_load_ushort v100, v[8:9] offset:512
	v_or_b32_e32 v4, 11, v30
	v_mad_i64_i32 v[4:5], s[2:3], v4, s18, v[2:3]
	v_or_b32_e32 v6, 12, v30
	v_or_b32_e32 v10, 13, v30
	v_lshl_add_u64 v[4:5], v[4:5], 0, v[0:1]
	v_mad_i64_i32 v[6:7], s[2:3], v6, s18, v[2:3]
	v_mad_i64_i32 v[10:11], s[2:3], v10, s18, v[2:3]
	v_lshl_add_u64 v[6:7], v[6:7], 0, v[0:1]
	v_lshl_add_u64 v[10:11], v[10:11], 0, v[0:1]
	flat_load_ushort v114, v[8:9] offset:1024
	flat_load_ushort v106, v[4:5]
	flat_load_ushort v103, v[4:5] offset:512
	flat_load_ushort v102, v[4:5] offset:1024
	flat_load_ushort v96, v[6:7]
	flat_load_ushort v92, v[6:7] offset:512
	flat_load_ushort v90, v[6:7] offset:1024
	flat_load_ushort v81, v[10:11]
	v_or_b32_e32 v4, 14, v30
	v_mad_i64_i32 v[4:5], s[2:3], v4, s18, v[2:3]
	v_or_b32_e32 v6, 15, v30
	v_lshl_add_u64 v[4:5], v[4:5], 0, v[0:1]
	v_mad_i64_i32 v[6:7], s[2:3], v6, s18, v[2:3]
	v_lshl_add_u64 v[6:7], v[6:7], 0, v[0:1]
	flat_load_ushort v94, v[10:11] offset:512
	flat_load_ushort v91, v[10:11] offset:1024
	flat_load_ushort v86, v[4:5]
	flat_load_ushort v79, v[4:5] offset:512
	flat_load_ushort v78, v[4:5] offset:1024
	flat_load_ushort v77, v[6:7]
	flat_load_ushort v76, v[6:7] offset:512
	flat_load_ushort v75, v[6:7] offset:1024
	v_or_b32_e32 v4, 16, v30
	v_mad_i64_i32 v[4:5], s[2:3], v4, s18, v[2:3]
	v_or_b32_e32 v6, 17, v30
	v_or_b32_e32 v8, 18, v30
	v_lshl_add_u64 v[4:5], v[4:5], 0, v[0:1]
	v_mad_i64_i32 v[6:7], s[2:3], v6, s18, v[2:3]
	v_mad_i64_i32 v[8:9], s[2:3], v8, s18, v[2:3]
	v_lshl_add_u64 v[6:7], v[6:7], 0, v[0:1]
	v_lshl_add_u64 v[8:9], v[8:9], 0, v[0:1]
	flat_load_ushort v74, v[4:5]
	flat_load_ushort v73, v[4:5] offset:512
	flat_load_ushort v72, v[4:5] offset:1024
	flat_load_ushort v71, v[6:7]
	flat_load_ushort v70, v[6:7] offset:512
	flat_load_ushort v69, v[6:7] offset:1024
	flat_load_ushort v68, v[8:9]
	flat_load_ushort v67, v[8:9] offset:512
	v_or_b32_e32 v4, 19, v30
	v_mad_i64_i32 v[4:5], s[2:3], v4, s18, v[2:3]
	v_lshl_add_u64 v[10:11], v[4:5], 0, v[0:1]
	v_or_b32_e32 v4, 20, v30
	v_mad_i64_i32 v[4:5], s[2:3], v4, s18, v[2:3]
	v_lshl_add_u64 v[12:13], v[4:5], 0, v[0:1]
	v_or_b32_e32 v4, 21, v30
	v_and_b32_e32 v89, 31, v109
	v_mad_i64_i32 v[4:5], s[2:3], v4, s18, v[2:3]
	v_bfe_u32 v93, v109, 5, 1
	v_or_b32_e32 v16, s7, v89
	v_lshl_add_u64 v[14:15], v[4:5], 0, v[0:1]
	v_mad_i64_i32 v[4:5], s[2:3], v16, s18, v[2:3]
	v_lshlrev_b32_e32 v82, 4, v93
	v_lshl_add_u64 v[4:5], v[4:5], 0, v[82:83]
	s_movk_i32 s42, 0x1000
	v_add_co_u32_e32 v4, vcc, s42, v4
	v_lshl_or_b32 v190, s6, 5, v89
	s_nop 0
	v_addc_co_u32_e32 v5, vcc, 0, v5, vcc
	flat_load_dwordx4 v[4:7], v[4:5] offset:3072
	v_lshl_add_u32 v18, v93, 11, v190
	v_or_b32_e32 v16, 32, v16
	v_ashrrev_i32_e32 v19, 31, v18
	v_mad_i64_i32 v[16:17], s[2:3], v16, s18, v[2:3]
	v_lshl_add_u64 v[20:21], v[18:19], 2, s[40:41]
	v_add_u32_e32 v22, 0x400, v18
	v_add_u32_e32 v24, 0x500, v18
	v_add_u32_e32 v26, 0x600, v18
	v_add_u32_e32 v18, 0x700, v18
	v_lshl_add_u64 v[16:17], v[16:17], 0, v[82:83]
	v_ashrrev_i32_e32 v25, 31, v24
	v_ashrrev_i32_e32 v19, 31, v18
	v_add_co_u32_e32 v16, vcc, s42, v16
	v_ashrrev_i32_e32 v23, 31, v22
	v_lshl_add_u64 v[24:25], v[24:25], 2, s[40:41]
	v_ashrrev_i32_e32 v27, 31, v26
	v_lshl_add_u64 v[18:19], v[18:19], 2, s[40:41]
	v_ashrrev_i32_e32 v191, 31, v190
	v_addc_co_u32_e32 v17, vcc, 0, v17, vcc
	v_lshl_add_u64 v[22:23], v[22:23], 2, s[40:41]
	v_lshl_add_u64 v[26:27], v[26:27], 2, s[40:41]
	global_load_dword v32, v[20:21], off
	global_load_dword v33, v[20:21], off offset:1024
	global_load_dword v80, v[20:21], off offset:2048
	global_load_dword v83, v[20:21], off offset:3072
	global_load_dword v88, v[22:23], off
	s_nop 0
	global_load_dword v24, v[24:25], off
	s_nop 0
	global_load_dword v25, v[26:27], off
	global_load_dword v95, v[18:19], off
	s_nop 0
	flat_load_dwordx4 v[18:21], v[16:17] offset:3072
	flat_load_ushort v186, v[8:9] offset:1024
	flat_load_ushort v184, v[10:11]
	flat_load_ushort v167, v[10:11] offset:512
	flat_load_ushort v166, v[10:11] offset:1024
	flat_load_ushort v162, v[12:13]
	flat_load_ushort v159, v[12:13] offset:512
	flat_load_ushort v157, v[12:13] offset:1024
	flat_load_ushort v149, v[14:15]
	v_lshl_add_u64 v[8:9], v[190:191], 2, s[38:39]
	global_load_dword v188, v[8:9], off
	v_or_b32_e32 v10, 22, v30
	v_mad_i64_i32 v[8:9], s[2:3], v10, s18, v[2:3]
	v_or_b32_e32 v10, 23, v30
	v_lshl_add_u64 v[8:9], v[8:9], 0, v[0:1]
	v_mad_i64_i32 v[10:11], s[2:3], v10, s18, v[2:3]
	v_lshl_add_u64 v[10:11], v[10:11], 0, v[0:1]
	flat_load_ushort v165, v[14:15] offset:512
	flat_load_ushort v164, v[14:15] offset:1024
	flat_load_ushort v158, v[8:9]
	flat_load_ushort v154, v[8:9] offset:512
	flat_load_ushort v153, v[8:9] offset:1024
	flat_load_ushort v147, v[10:11]
	flat_load_ushort v143, v[10:11] offset:512
	flat_load_ushort v142, v[10:11] offset:1024
	v_or_b32_e32 v8, 24, v30
	v_mad_i64_i32 v[8:9], s[2:3], v8, s18, v[2:3]
	v_or_b32_e32 v10, 25, v30
	v_or_b32_e32 v12, 26, v30
	v_lshl_add_u64 v[8:9], v[8:9], 0, v[0:1]
	v_mad_i64_i32 v[10:11], s[2:3], v10, s18, v[2:3]
	v_mad_i64_i32 v[12:13], s[2:3], v12, s18, v[2:3]
	v_lshl_add_u64 v[10:11], v[10:11], 0, v[0:1]
	v_lshl_add_u64 v[12:13], v[12:13], 0, v[0:1]
	flat_load_ushort v136, v[8:9]
	flat_load_ushort v135, v[8:9] offset:512
	flat_load_ushort v134, v[8:9] offset:1024
	flat_load_ushort v129, v[10:11]
	flat_load_ushort v128, v[10:11] offset:512
	flat_load_ushort v127, v[10:11] offset:1024
	flat_load_ushort v121, v[12:13]
	flat_load_ushort v117, v[12:13] offset:512
	v_or_b32_e32 v8, 27, v30
	v_mad_i64_i32 v[8:9], s[2:3], v8, s18, v[2:3]
	v_or_b32_e32 v10, 28, v30
	v_or_b32_e32 v14, 29, v30
	v_lshl_add_u64 v[8:9], v[8:9], 0, v[0:1]
	v_mad_i64_i32 v[10:11], s[2:3], v10, s18, v[2:3]
	v_mad_i64_i32 v[14:15], s[2:3], v14, s18, v[2:3]
	v_lshl_add_u64 v[10:11], v[10:11], 0, v[0:1]
	v_lshl_add_u64 v[26:27], v[14:15], 0, v[0:1]
	flat_load_ushort v125, v[12:13] offset:1024
	flat_load_ushort v118, v[8:9]
	flat_load_ushort v116, v[8:9] offset:512
	flat_load_ushort v115, v[8:9] offset:1024
	flat_load_ushort v110, v[10:11]
	flat_load_ushort v107, v[10:11] offset:512
	flat_load_ushort v104, v[10:11] offset:1024
	flat_load_ushort v98, v[26:27]
	v_or_b32_e32 v8, 30, v30
	v_mad_i64_i32 v[8:9], s[2:3], v8, s18, v[2:3]
	v_lshl_add_u64 v[28:29], v[8:9], 0, v[0:1]
	v_or_b32_e32 v8, 31, v30
	v_mad_i64_i32 v[2:3], s[2:3], v8, s18, v[2:3]
	v_lshl_add_u64 v[30:31], v[2:3], 0, v[0:1]
	v_lshlrev_b32_e32 v190, 1, v190
	v_mul_u32_u24_e32 v191, 0x840, v93
	v_add3_u32 v192, v189, v190, v191
	s_mov_b32 s2, 0x3d800000
	s_waitcnt vmcnt(0)
	v_cvt_pk_bf16_f32 v22, v32, v33
	v_cvt_pk_bf16_f32 v23, v80, v83
	v_cvt_pk_bf16_f32 v24, v88, v24
	v_cvt_pk_bf16_f32 v25, v25, v95
	flat_load_ushort v108, v[26:27] offset:512
	flat_load_ushort v105, v[26:27] offset:1024
	flat_load_ushort v99, v[28:29]
	flat_load_ushort v97, v[28:29] offset:512
	flat_load_ushort v95, v[28:29] offset:1024
	flat_load_ushort v88, v[30:31]
	flat_load_ushort v83, v[30:31] offset:512
	flat_load_ushort v80, v[30:31] offset:1024
	s_waitcnt lgkmcnt(0)
	v_mfma_f32_32x32x16_bf16 v[2:17], v[4:7], v[22:25], 0
	v_mfma_f32_32x32x16_bf16 v[18:33], v[18:21], v[22:25], 0
	s_nop 10
	v_add_f32_e32 v2, v188, v2
	v_cvt_pk_bf16_f32 v2, v2, s0
	ds_write_b16 v192, v2
	v_add_f32_e32 v2, v188, v18
	v_cvt_pk_bf16_f32 v2, v2, s0
	v_add3_u32 v18, v189, v191, v190
	ds_write_b16 v18, v2 offset:16896
	v_add_f32_e32 v2, v188, v3
	v_cvt_pk_bf16_f32 v2, v2, s0
	ds_write_b16 v192, v2 offset:528
	v_add_f32_e32 v2, v188, v19
	v_cvt_pk_bf16_f32 v2, v2, s0
	ds_write_b16 v18, v2 offset:17424
	v_add_f32_e32 v2, v188, v4
	v_cvt_pk_bf16_f32 v2, v2, s0
	ds_write_b16 v192, v2 offset:1056
	v_add_f32_e32 v2, v188, v20
	v_cvt_pk_bf16_f32 v2, v2, s0
	ds_write_b16 v18, v2 offset:17952
	v_add_f32_e32 v2, v188, v5
	v_cvt_pk_bf16_f32 v2, v2, s0
	ds_write_b16 v192, v2 offset:1584
	v_add_f32_e32 v2, v188, v21
	v_cvt_pk_bf16_f32 v2, v2, s0
	ds_write_b16 v18, v2 offset:18480
	v_add_f32_e32 v2, v188, v6
	v_cvt_pk_bf16_f32 v2, v2, s0
	ds_write_b16 v192, v2 offset:4224
	v_add_f32_e32 v2, v188, v22
	v_cvt_pk_bf16_f32 v2, v2, s0
	ds_write_b16 v18, v2 offset:21120
	v_add_f32_e32 v2, v188, v7
	v_cvt_pk_bf16_f32 v2, v2, s0
	ds_write_b16 v192, v2 offset:4752
	v_add_f32_e32 v2, v188, v23
	v_cvt_pk_bf16_f32 v2, v2, s0
	ds_write_b16 v18, v2 offset:21648
	v_add_f32_e32 v2, v188, v8
	v_cvt_pk_bf16_f32 v2, v2, s0
	ds_write_b16 v192, v2 offset:5280
	v_add_f32_e32 v2, v188, v24
	v_cvt_pk_bf16_f32 v2, v2, s0
	ds_write_b16 v18, v2 offset:22176
	v_add_f32_e32 v2, v188, v9
	v_cvt_pk_bf16_f32 v2, v2, s0
	ds_write_b16 v192, v2 offset:5808
	v_add_f32_e32 v2, v188, v25
	v_cvt_pk_bf16_f32 v2, v2, s0
	ds_write_b16 v18, v2 offset:22704
	v_add_f32_e32 v2, v188, v10
	v_cvt_pk_bf16_f32 v2, v2, s0
	ds_write_b16 v192, v2 offset:8448
	v_add_f32_e32 v2, v188, v26
	v_cvt_pk_bf16_f32 v2, v2, s0
	ds_write_b16 v18, v2 offset:25344
	v_add_f32_e32 v2, v188, v11
	v_cvt_pk_bf16_f32 v2, v2, s0
	ds_write_b16 v192, v2 offset:8976
	v_add_f32_e32 v2, v188, v27
	v_cvt_pk_bf16_f32 v2, v2, s0
	ds_write_b16 v18, v2 offset:25872
	v_add_f32_e32 v2, v188, v12
	v_cvt_pk_bf16_f32 v2, v2, s0
	ds_write_b16 v192, v2 offset:9504
	v_add_f32_e32 v2, v188, v28
	v_cvt_pk_bf16_f32 v2, v2, s0
	ds_write_b16 v18, v2 offset:26400
	v_add_f32_e32 v2, v188, v13
	v_cvt_pk_bf16_f32 v2, v2, s0
	ds_write_b16 v192, v2 offset:10032
	v_add_f32_e32 v2, v188, v29
	v_cvt_pk_bf16_f32 v2, v2, s0
	ds_write_b16 v18, v2 offset:26928
	v_add_f32_e32 v2, v188, v14
	v_cvt_pk_bf16_f32 v2, v2, s0
	ds_write_b16 v192, v2 offset:12672
	v_add_f32_e32 v2, v188, v30
	v_cvt_pk_bf16_f32 v2, v2, s0
	ds_write_b16 v18, v2 offset:29568
	v_add_f32_e32 v2, v188, v15
	v_cvt_pk_bf16_f32 v2, v2, s0
	ds_write_b16 v192, v2 offset:13200
	v_add_f32_e32 v2, v188, v31
	v_cvt_pk_bf16_f32 v2, v2, s0
	ds_write_b16 v18, v2 offset:30096
	v_add_f32_e32 v2, v188, v16
	v_cvt_pk_bf16_f32 v2, v2, s0
	ds_write_b16 v192, v2 offset:13728
	v_add_f32_e32 v2, v188, v32
	v_cvt_pk_bf16_f32 v2, v2, s0
	ds_write_b16 v18, v2 offset:30624
	v_add_f32_e32 v2, v188, v17
	v_cvt_pk_bf16_f32 v2, v2, s0
	ds_write_b16 v192, v2 offset:14256
	v_add_f32_e32 v2, v188, v33
	v_mul_i32_i24_e32 v188, 0x4200, v160
	v_cvt_pk_bf16_f32 v2, v2, s0
	v_add3_u32 v24, v189, v0, v188
	ds_write_b16 v18, v2 offset:31152
	s_waitcnt lgkmcnt(0)
	s_barrier
	ds_read_u16 v2, v24
	ds_read_u16 v3, v24 offset:528
	ds_read_u16 v4, v24 offset:1056
	ds_read_u16 v5, v24 offset:1584
	ds_read_u16 v6, v24 offset:2112
	ds_read_u16 v7, v24 offset:2640
	ds_read_u16 v8, v24 offset:3168
	ds_read_u16 v9, v24 offset:3696
	s_waitcnt lgkmcnt(0)
	v_lshlrev_b32_e32 v2, 16, v2
	v_mul_f32_e64 v10, |v2|, s19
	v_exp_f32_e32 v10, v10
	v_lshlrev_b32_e32 v3, 16, v3
	v_mul_f32_e64 v12, |v3|, s19
	v_exp_f32_e32 v12, v12
	v_add_f32_e32 v10, 1.0, v10
	v_cmp_gt_f32_e32 vcc, s96, v10
	v_max_f32_e32 v2, v2, v2
	v_min_f32_e32 v2, 0, v2
	v_cndmask_b32_e64 v11, 0, 32, vcc
	v_ldexp_f32 v10, v10, v11
	v_log_f32_e32 v10, v10
	v_lshlrev_b32_e32 v4, 16, v4
	v_max_f32_e32 v3, v3, v3
	v_min_f32_e32 v3, 0, v3
	v_mul_f32_e32 v11, 0x3f317217, v10
	v_fma_f32 v11, v10, s97, -v11
	v_fmac_f32_e32 v11, 0x3377d1cf, v10
	v_fmac_f32_e32 v11, 0x3f317217, v10
	v_cmp_lt_f32_e64 s[38:39], |v10|, s15
	v_lshlrev_b32_e32 v5, 16, v5
	v_lshlrev_b32_e32 v6, 16, v6
	v_cndmask_b32_e64 v10, v10, v11, s[38:39]
	v_cndmask_b32_e32 v11, 0, v179, vcc
	v_sub_f32_e32 v10, v10, v11
	v_add_f32_e32 v11, 1.0, v12
	v_cmp_gt_f32_e32 vcc, s96, v11
	v_sub_f32_e32 v2, v2, v10
	v_lshlrev_b32_e32 v7, 16, v7
	v_cndmask_b32_e64 v12, 0, 32, vcc
	v_ldexp_f32 v11, v11, v12
	v_log_f32_e32 v11, v11
	v_mul_f32_e64 v12, |v4|, s19
	v_exp_f32_e32 v12, v12
	v_max_f32_e32 v4, v4, v4
	v_mul_f32_e32 v10, 0x3f317217, v11
	v_fma_f32 v10, v11, s97, -v10
	v_fmac_f32_e32 v10, 0x3377d1cf, v11
	v_fmac_f32_e32 v10, 0x3f317217, v11
	v_cmp_lt_f32_e64 s[38:39], |v11|, s15
	v_min_f32_e32 v4, 0, v4
	v_lshlrev_b32_e32 v8, 16, v8
	v_cndmask_b32_e64 v10, v11, v10, s[38:39]
	v_cndmask_b32_e32 v11, 0, v179, vcc
	v_sub_f32_e32 v10, v10, v11
	v_sub_f32_e32 v3, v3, v10
	v_add_f32_e32 v10, 1.0, v12
	v_cmp_gt_f32_e32 vcc, s96, v10
	v_mul_f32_e64 v12, |v5|, s19
	v_exp_f32_e32 v12, v12
	v_cndmask_b32_e64 v11, 0, 32, vcc
	v_ldexp_f32 v10, v10, v11
	v_log_f32_e32 v10, v10
	v_max_f32_e32 v5, v5, v5
	v_min_f32_e32 v5, 0, v5
	v_lshlrev_b32_e32 v9, 16, v9
	v_mul_f32_e32 v11, 0x3f317217, v10
	v_fma_f32 v11, v10, s97, -v11
	v_fmac_f32_e32 v11, 0x3377d1cf, v10
	v_fmac_f32_e32 v11, 0x3f317217, v10
	v_cmp_lt_f32_e64 s[38:39], |v10|, s15
	v_fma_f32 v2, v2, s2, 0
	v_fmamk_f32 v3, v3, 0x3d800000, v2
	v_cndmask_b32_e64 v10, v10, v11, s[38:39]
	v_cndmask_b32_e32 v11, 0, v179, vcc
	v_sub_f32_e32 v10, v10, v11
	v_add_f32_e32 v11, 1.0, v12
	v_cmp_gt_f32_e32 vcc, s96, v11
	v_sub_f32_e32 v4, v4, v10
	v_fmamk_f32 v4, v4, 0x3d800000, v3
	v_cndmask_b32_e64 v12, 0, 32, vcc
	v_ldexp_f32 v11, v11, v12
	v_log_f32_e32 v11, v11
	v_mul_f32_e64 v12, |v6|, s19
	v_exp_f32_e32 v12, v12
	v_max_f32_e32 v6, v6, v6
	v_mul_f32_e32 v10, 0x3f317217, v11
	v_fma_f32 v10, v11, s97, -v10
	v_fmac_f32_e32 v10, 0x3377d1cf, v11
	v_fmac_f32_e32 v10, 0x3f317217, v11
	v_cmp_lt_f32_e64 s[38:39], |v11|, s15
	v_min_f32_e32 v6, 0, v6
	s_movk_i32 s2, 0xff
	v_cndmask_b32_e64 v10, v11, v10, s[38:39]
	v_cndmask_b32_e32 v11, 0, v179, vcc
	v_sub_f32_e32 v10, v10, v11
	v_sub_f32_e32 v5, v5, v10
	v_add_f32_e32 v10, 1.0, v12
	v_cmp_gt_f32_e32 vcc, s96, v10
	v_mul_f32_e64 v12, |v7|, s19
	v_exp_f32_e32 v12, v12
	v_cndmask_b32_e64 v11, 0, 32, vcc
	v_ldexp_f32 v10, v10, v11
	v_log_f32_e32 v10, v10
	v_max_f32_e32 v7, v7, v7
	v_min_f32_e32 v7, 0, v7
	v_fmamk_f32 v5, v5, 0x3d800000, v4
	v_mul_f32_e32 v11, 0x3f317217, v10
	v_fma_f32 v11, v10, s97, -v11
	v_fmac_f32_e32 v11, 0x3377d1cf, v10
	v_fmac_f32_e32 v11, 0x3f317217, v10
	v_cmp_lt_f32_e64 s[38:39], |v10|, s15
	s_nop 1
	v_cndmask_b32_e64 v10, v10, v11, s[38:39]
	v_cndmask_b32_e32 v11, 0, v179, vcc
	v_sub_f32_e32 v10, v10, v11
	v_add_f32_e32 v11, 1.0, v12
	v_cmp_gt_f32_e32 vcc, s96, v11
	v_sub_f32_e32 v6, v6, v10
	v_fmamk_f32 v6, v6, 0x3d800000, v5
	v_cndmask_b32_e64 v12, 0, 32, vcc
	v_ldexp_f32 v11, v11, v12
	v_log_f32_e32 v11, v11
	v_mul_f32_e64 v12, |v8|, s19
	v_exp_f32_e32 v12, v12
	v_max_f32_e32 v8, v8, v8
	v_mul_f32_e32 v10, 0x3f317217, v11
	v_fma_f32 v10, v11, s97, -v10
	v_fmac_f32_e32 v10, 0x3377d1cf, v11
	v_fmac_f32_e32 v10, 0x3f317217, v11
	v_cmp_lt_f32_e64 s[38:39], |v11|, s15
	v_min_f32_e32 v8, 0, v8
	s_nop 0
	v_cndmask_b32_e64 v10, v11, v10, s[38:39]
	v_cndmask_b32_e32 v11, 0, v179, vcc
	v_sub_f32_e32 v10, v10, v11
	v_sub_f32_e32 v7, v7, v10
	v_add_f32_e32 v10, 1.0, v12
	v_cmp_gt_f32_e32 vcc, s96, v10
	v_mul_f32_e64 v12, |v9|, s19
	v_exp_f32_e32 v12, v12
	v_cndmask_b32_e64 v11, 0, 32, vcc
	v_ldexp_f32 v10, v10, v11
	v_log_f32_e32 v10, v10
	v_max_f32_e32 v9, v9, v9
	v_min_f32_e32 v9, 0, v9
	v_fmamk_f32 v7, v7, 0x3d800000, v6
	v_mul_f32_e32 v11, 0x3f317217, v10
	v_fma_f32 v11, v10, s97, -v11
	v_fmac_f32_e32 v11, 0x3377d1cf, v10
	v_fmac_f32_e32 v11, 0x3f317217, v10
	v_cmp_lt_f32_e64 s[38:39], |v10|, s15
	s_nop 1
	v_cndmask_b32_e64 v10, v10, v11, s[38:39]
	v_cndmask_b32_e32 v11, 0, v179, vcc
	v_sub_f32_e32 v10, v10, v11
	v_add_f32_e32 v11, 1.0, v12
	v_cmp_gt_f32_e32 vcc, s96, v11
	v_sub_f32_e32 v8, v8, v10
	v_fmamk_f32 v8, v8, 0x3d800000, v7
	v_cndmask_b32_e64 v12, 0, 32, vcc
	v_ldexp_f32 v11, v11, v12
	v_log_f32_e32 v11, v11
	ds_read_u16 v12, v24 offset:4224
	ds_read_u16 v13, v24 offset:4752
	ds_read_u16 v14, v24 offset:5280
	ds_read_u16 v15, v24 offset:5808
	ds_read_u16 v16, v24 offset:6336
	ds_read_u16 v17, v24 offset:6864
	ds_read_u16 v18, v24 offset:7392
	ds_read_u16 v19, v24 offset:7920
	s_waitcnt lgkmcnt(0)
	v_lshlrev_b32_e32 v12, 16, v12
	v_mul_f32_e64 v20, |v12|, s19
	v_mul_f32_e32 v10, 0x3f317217, v11
	v_fma_f32 v10, v11, s97, -v10
	v_fmac_f32_e32 v10, 0x3377d1cf, v11
	v_exp_f32_e32 v20, v20
	v_fmac_f32_e32 v10, 0x3f317217, v11
	v_cmp_lt_f32_e64 s[38:39], |v11|, s15
	v_lshlrev_b32_e32 v13, 16, v13
	v_lshlrev_b32_e32 v14, 16, v14
	v_cndmask_b32_e64 v10, v11, v10, s[38:39]
	v_cndmask_b32_e32 v11, 0, v179, vcc
	v_sub_f32_e32 v10, v10, v11
	v_sub_f32_e32 v9, v9, v10
	v_add_f32_e32 v10, 1.0, v20
	v_cmp_gt_f32_e32 vcc, s96, v10
	v_mul_f32_e64 v20, |v13|, s19
	v_exp_f32_e32 v20, v20
	v_cndmask_b32_e64 v11, 0, 32, vcc
	v_ldexp_f32 v10, v10, v11
	v_log_f32_e32 v10, v10
	v_max_f32_e32 v11, v12, v12
	v_min_f32_e32 v11, 0, v11
	v_lshlrev_b32_e32 v15, 16, v15
	v_mul_f32_e32 v12, 0x3f317217, v10
	v_fma_f32 v12, v10, s97, -v12
	v_fmac_f32_e32 v12, 0x3377d1cf, v10
	v_fmac_f32_e32 v12, 0x3f317217, v10
	v_cmp_lt_f32_e64 s[38:39], |v10|, s15
	v_lshlrev_b32_e32 v16, 16, v16
	v_lshlrev_b32_e32 v17, 16, v17
	v_cndmask_b32_e64 v10, v10, v12, s[38:39]
	v_cndmask_b32_e32 v12, 0, v179, vcc
	v_sub_f32_e32 v10, v10, v12
	v_add_f32_e32 v12, 1.0, v20
	v_cmp_gt_f32_e32 vcc, s96, v12
	v_sub_f32_e32 v10, v11, v10
	v_max_f32_e32 v11, v13, v13
	v_cndmask_b32_e64 v20, 0, 32, vcc
	v_ldexp_f32 v12, v12, v20
	v_log_f32_e32 v12, v12
	v_mul_f32_e64 v20, |v14|, s19
	v_exp_f32_e32 v20, v20
	v_min_f32_e32 v11, 0, v11
	v_mul_f32_e32 v13, 0x3f317217, v12
	v_fma_f32 v13, v12, s97, -v13
	v_fmac_f32_e32 v13, 0x3377d1cf, v12
	v_fmac_f32_e32 v13, 0x3f317217, v12
	v_cmp_lt_f32_e64 s[38:39], |v12|, s15
	v_lshlrev_b32_e32 v18, 16, v18
	v_lshlrev_b32_e32 v19, 16, v19
	v_cndmask_b32_e64 v12, v12, v13, s[38:39]
	v_cndmask_b32_e32 v13, 0, v179, vcc
	v_sub_f32_e32 v12, v12, v13
	v_sub_f32_e32 v11, v11, v12
	v_add_f32_e32 v12, 1.0, v20
	v_cmp_gt_f32_e32 vcc, s96, v12
	v_mul_f32_e64 v20, |v15|, s19
	v_exp_f32_e32 v20, v20
	v_cndmask_b32_e64 v13, 0, 32, vcc
	v_ldexp_f32 v12, v12, v13
	v_log_f32_e32 v12, v12
	v_max_f32_e32 v13, v14, v14
	v_min_f32_e32 v13, 0, v13
	v_fmamk_f32 v9, v9, 0x3d800000, v8
	v_mul_f32_e32 v14, 0x3f317217, v12
	v_fma_f32 v14, v12, s97, -v14
	v_fmac_f32_e32 v14, 0x3377d1cf, v12
	v_fmac_f32_e32 v14, 0x3f317217, v12
	v_cmp_lt_f32_e64 s[38:39], |v12|, s15
	v_fmamk_f32 v10, v10, 0x3d800000, v9
	v_fmamk_f32 v11, v11, 0x3d800000, v10
	v_cndmask_b32_e64 v12, v12, v14, s[38:39]
	v_cndmask_b32_e32 v14, 0, v179, vcc
	v_sub_f32_e32 v12, v12, v14
	v_add_f32_e32 v14, 1.0, v20
	v_cmp_gt_f32_e32 vcc, s96, v14
	v_sub_f32_e32 v12, v13, v12
	v_max_f32_e32 v13, v15, v15
	v_cndmask_b32_e64 v20, 0, 32, vcc
	v_ldexp_f32 v14, v14, v20
	v_log_f32_e32 v14, v14
	v_mul_f32_e64 v20, |v16|, s19
	v_exp_f32_e32 v20, v20
	v_min_f32_e32 v13, 0, v13
	v_mul_f32_e32 v15, 0x3f317217, v14
	v_fma_f32 v15, v14, s97, -v15
	v_fmac_f32_e32 v15, 0x3377d1cf, v14
	v_fmac_f32_e32 v15, 0x3f317217, v14
	v_cmp_lt_f32_e64 s[38:39], |v14|, s15
	v_fmamk_f32 v12, v12, 0x3d800000, v11
	s_nop 0
	v_cndmask_b32_e64 v14, v14, v15, s[38:39]
	v_cndmask_b32_e32 v15, 0, v179, vcc
	v_sub_f32_e32 v14, v14, v15
	v_sub_f32_e32 v13, v13, v14
	v_add_f32_e32 v14, 1.0, v20
	v_cmp_gt_f32_e32 vcc, s96, v14
	v_mul_f32_e64 v20, |v17|, s19
	v_exp_f32_e32 v20, v20
	v_cndmask_b32_e64 v15, 0, 32, vcc
	v_ldexp_f32 v14, v14, v15
	v_log_f32_e32 v14, v14
	v_max_f32_e32 v15, v16, v16
	v_min_f32_e32 v15, 0, v15
	v_fmamk_f32 v13, v13, 0x3d800000, v12
	v_mul_f32_e32 v16, 0x3f317217, v14
	v_fma_f32 v16, v14, s97, -v16
	v_fmac_f32_e32 v16, 0x3377d1cf, v14
	v_fmac_f32_e32 v16, 0x3f317217, v14
	v_cmp_lt_f32_e64 s[38:39], |v14|, s15
	s_nop 1
	v_cndmask_b32_e64 v14, v14, v16, s[38:39]
	v_cndmask_b32_e32 v16, 0, v179, vcc
	v_sub_f32_e32 v14, v14, v16
	v_add_f32_e32 v16, 1.0, v20
	v_cmp_gt_f32_e32 vcc, s96, v16
	v_sub_f32_e32 v14, v15, v14
	v_max_f32_e32 v15, v17, v17
	v_cndmask_b32_e64 v20, 0, 32, vcc
	v_ldexp_f32 v16, v16, v20
	v_log_f32_e32 v16, v16
	v_mul_f32_e64 v20, |v18|, s19
	v_exp_f32_e32 v20, v20
	v_min_f32_e32 v15, 0, v15
	v_mul_f32_e32 v17, 0x3f317217, v16
	v_fma_f32 v17, v16, s97, -v17
	v_fmac_f32_e32 v17, 0x3377d1cf, v16
	v_fmac_f32_e32 v17, 0x3f317217, v16
	v_cmp_lt_f32_e64 s[38:39], |v16|, s15
	v_fmamk_f32 v14, v14, 0x3d800000, v13
	s_nop 0
	v_cndmask_b32_e64 v16, v16, v17, s[38:39]
	v_cndmask_b32_e32 v17, 0, v179, vcc
	v_sub_f32_e32 v16, v16, v17
	v_sub_f32_e32 v15, v15, v16
	v_add_f32_e32 v16, 1.0, v20
	v_cmp_gt_f32_e32 vcc, s96, v16
	v_mul_f32_e64 v20, |v19|, s19
	v_exp_f32_e32 v20, v20
	v_cndmask_b32_e64 v17, 0, 32, vcc
	v_ldexp_f32 v16, v16, v17
	v_log_f32_e32 v16, v16
	v_max_f32_e32 v17, v18, v18
	v_min_f32_e32 v17, 0, v17
	v_fmamk_f32 v15, v15, 0x3d800000, v14
	v_mul_f32_e32 v18, 0x3f317217, v16
	v_fma_f32 v18, v16, s97, -v18
	v_fmac_f32_e32 v18, 0x3377d1cf, v16
	v_fmac_f32_e32 v18, 0x3f317217, v16
	v_cmp_lt_f32_e64 s[38:39], |v16|, s15
	s_nop 1
	v_cndmask_b32_e64 v16, v16, v18, s[38:39]
	v_cndmask_b32_e32 v18, 0, v179, vcc
	v_sub_f32_e32 v16, v16, v18
	v_add_f32_e32 v18, 1.0, v20
	v_cmp_gt_f32_e32 vcc, s96, v18
	v_sub_f32_e32 v16, v17, v16
	v_max_f32_e32 v17, v19, v19
	v_cndmask_b32_e64 v20, 0, 32, vcc
	v_ldexp_f32 v18, v18, v20
	v_log_f32_e32 v18, v18
	ds_read_u16 v20, v24 offset:8448
	ds_read_u16 v21, v24 offset:8976
	ds_read_u16 v22, v24 offset:9504
	ds_read_u16 v23, v24 offset:10032
	ds_read_u16 v25, v24 offset:10560
	ds_read_u16 v26, v24 offset:11088
	ds_read_u16 v27, v24 offset:11616
	ds_read_u16 v28, v24 offset:12144
	s_waitcnt lgkmcnt(0)
	v_lshlrev_b32_e32 v20, 16, v20
	v_mul_f32_e64 v29, |v20|, s19
	v_mul_f32_e32 v19, 0x3f317217, v18
	v_fma_f32 v19, v18, s97, -v19
	v_fmac_f32_e32 v19, 0x3377d1cf, v18
	v_exp_f32_e32 v29, v29
	v_fmac_f32_e32 v19, 0x3f317217, v18
	v_cmp_lt_f32_e64 s[38:39], |v18|, s15
	v_min_f32_e32 v17, 0, v17
	v_lshlrev_b32_e32 v21, 16, v21
	v_cndmask_b32_e64 v18, v18, v19, s[38:39]
	v_cndmask_b32_e32 v19, 0, v179, vcc
	v_sub_f32_e32 v18, v18, v19
	v_sub_f32_e32 v17, v17, v18
	v_add_f32_e32 v18, 1.0, v29
	v_cmp_gt_f32_e32 vcc, s96, v18
	v_mul_f32_e64 v29, |v21|, s19
	v_exp_f32_e32 v29, v29
	v_cndmask_b32_e64 v19, 0, 32, vcc
	v_ldexp_f32 v18, v18, v19
	v_log_f32_e32 v18, v18
	v_max_f32_e32 v19, v20, v20
	v_min_f32_e32 v19, 0, v19
	v_lshlrev_b32_e32 v22, 16, v22
	v_mul_f32_e32 v20, 0x3f317217, v18
	v_fma_f32 v20, v18, s97, -v20
	v_fmac_f32_e32 v20, 0x3377d1cf, v18
	v_fmac_f32_e32 v20, 0x3f317217, v18
	v_cmp_lt_f32_e64 s[38:39], |v18|, s15
	v_lshlrev_b32_e32 v23, 16, v23
	v_lshlrev_b32_e32 v25, 16, v25
	v_cndmask_b32_e64 v18, v18, v20, s[38:39]
	v_cndmask_b32_e32 v20, 0, v179, vcc
	v_sub_f32_e32 v18, v18, v20
	v_add_f32_e32 v20, 1.0, v29
	v_cmp_gt_f32_e32 vcc, s96, v20
	v_sub_f32_e32 v18, v19, v18
	v_max_f32_e32 v19, v21, v21
	v_cndmask_b32_e64 v29, 0, 32, vcc
	v_ldexp_f32 v20, v20, v29
	v_log_f32_e32 v20, v20
	v_mul_f32_e64 v29, |v22|, s19
	v_exp_f32_e32 v29, v29
	v_min_f32_e32 v19, 0, v19
	v_mul_f32_e32 v21, 0x3f317217, v20
	v_fma_f32 v21, v20, s97, -v21
	v_fmac_f32_e32 v21, 0x3377d1cf, v20
	v_fmac_f32_e32 v21, 0x3f317217, v20
	v_cmp_lt_f32_e64 s[38:39], |v20|, s15
	v_lshlrev_b32_e32 v26, 16, v26
	v_lshlrev_b32_e32 v27, 16, v27
	v_cndmask_b32_e64 v20, v20, v21, s[38:39]
	v_cndmask_b32_e32 v21, 0, v179, vcc
	v_sub_f32_e32 v20, v20, v21
	v_sub_f32_e32 v19, v19, v20
	v_add_f32_e32 v20, 1.0, v29
	v_cmp_gt_f32_e32 vcc, s96, v20
	v_mul_f32_e64 v29, |v23|, s19
	v_exp_f32_e32 v29, v29
	v_cndmask_b32_e64 v21, 0, 32, vcc
	v_ldexp_f32 v20, v20, v21
	v_log_f32_e32 v20, v20
	v_max_f32_e32 v21, v22, v22
	v_min_f32_e32 v21, 0, v21
	v_lshlrev_b32_e32 v28, 16, v28
	v_mul_f32_e32 v22, 0x3f317217, v20
	v_fma_f32 v22, v20, s97, -v22
	v_fmac_f32_e32 v22, 0x3377d1cf, v20
	v_fmac_f32_e32 v22, 0x3f317217, v20
	v_cmp_lt_f32_e64 s[38:39], |v20|, s15
	v_fmamk_f32 v16, v16, 0x3d800000, v15
	v_fmamk_f32 v17, v17, 0x3d800000, v16
	v_cndmask_b32_e64 v20, v20, v22, s[38:39]
	v_cndmask_b32_e32 v22, 0, v179, vcc
	v_sub_f32_e32 v20, v20, v22
	v_add_f32_e32 v22, 1.0, v29
	v_cmp_gt_f32_e32 vcc, s96, v22
	v_sub_f32_e32 v20, v21, v20
	v_max_f32_e32 v21, v23, v23
	v_cndmask_b32_e64 v29, 0, 32, vcc
	v_ldexp_f32 v22, v22, v29
	v_log_f32_e32 v22, v22
	v_mul_f32_e64 v29, |v25|, s19
	v_exp_f32_e32 v29, v29
	v_min_f32_e32 v21, 0, v21
	v_mul_f32_e32 v23, 0x3f317217, v22
	v_fma_f32 v23, v22, s97, -v23
	v_fmac_f32_e32 v23, 0x3377d1cf, v22
	v_fmac_f32_e32 v23, 0x3f317217, v22
	v_cmp_lt_f32_e64 s[38:39], |v22|, s15
	v_fmamk_f32 v18, v18, 0x3d800000, v17
	v_fmamk_f32 v19, v19, 0x3d800000, v18
	v_cndmask_b32_e64 v22, v22, v23, s[38:39]
	v_cndmask_b32_e32 v23, 0, v179, vcc
	v_sub_f32_e32 v22, v22, v23
	v_sub_f32_e32 v21, v21, v22
	v_add_f32_e32 v22, 1.0, v29
	v_cmp_gt_f32_e32 vcc, s96, v22
	v_mul_f32_e64 v29, |v26|, s19
	v_exp_f32_e32 v29, v29
	v_cndmask_b32_e64 v23, 0, 32, vcc
	v_ldexp_f32 v22, v22, v23
	v_log_f32_e32 v22, v22
	v_max_f32_e32 v23, v25, v25
	v_min_f32_e32 v23, 0, v23
	v_fmamk_f32 v20, v20, 0x3d800000, v19
	v_mul_f32_e32 v25, 0x3f317217, v22
	v_fma_f32 v25, v22, s97, -v25
	v_fmac_f32_e32 v25, 0x3377d1cf, v22
	v_fmac_f32_e32 v25, 0x3f317217, v22
	v_cmp_lt_f32_e64 s[38:39], |v22|, s15
	v_fmamk_f32 v21, v21, 0x3d800000, v20
	s_nop 0
	v_cndmask_b32_e64 v22, v22, v25, s[38:39]
	v_cndmask_b32_e32 v25, 0, v179, vcc
	v_sub_f32_e32 v22, v22, v25
	v_add_f32_e32 v25, 1.0, v29
	v_cmp_gt_f32_e32 vcc, s96, v25
	v_sub_f32_e32 v22, v23, v22
	v_max_f32_e32 v23, v26, v26
	v_cndmask_b32_e64 v29, 0, 32, vcc
	v_ldexp_f32 v25, v25, v29
	v_log_f32_e32 v25, v25
	v_mul_f32_e64 v29, |v27|, s19
	v_exp_f32_e32 v29, v29
	v_min_f32_e32 v23, 0, v23
	v_mul_f32_e32 v26, 0x3f317217, v25
	v_fma_f32 v26, v25, s97, -v26
	v_fmac_f32_e32 v26, 0x3377d1cf, v25
	v_fmac_f32_e32 v26, 0x3f317217, v25
	v_cmp_lt_f32_e64 s[38:39], |v25|, s15
	v_fmamk_f32 v22, v22, 0x3d800000, v21
	s_nop 0
	v_cndmask_b32_e64 v25, v25, v26, s[38:39]
	v_cndmask_b32_e32 v26, 0, v179, vcc
	v_sub_f32_e32 v25, v25, v26
	v_sub_f32_e32 v23, v23, v25
	v_add_f32_e32 v25, 1.0, v29
	v_cmp_gt_f32_e32 vcc, s96, v25
	v_mul_f32_e64 v29, |v28|, s19
	v_exp_f32_e32 v29, v29
	v_cndmask_b32_e64 v26, 0, 32, vcc
	v_ldexp_f32 v25, v25, v26
	v_log_f32_e32 v25, v25
	v_max_f32_e32 v26, v27, v27
	v_min_f32_e32 v26, 0, v26
	v_fmamk_f32 v23, v23, 0x3d800000, v22
	v_mul_f32_e32 v27, 0x3f317217, v25
	v_fma_f32 v27, v25, s97, -v27
	v_fmac_f32_e32 v27, 0x3377d1cf, v25
	v_fmac_f32_e32 v27, 0x3f317217, v25
	v_cmp_lt_f32_e64 s[38:39], |v25|, s15
	s_nop 1
	v_cndmask_b32_e64 v25, v25, v27, s[38:39]
	v_cndmask_b32_e32 v27, 0, v179, vcc
	v_sub_f32_e32 v25, v25, v27
	v_add_f32_e32 v27, 1.0, v29
	v_cmp_gt_f32_e32 vcc, s96, v27
	v_sub_f32_e32 v25, v26, v25
	v_max_f32_e32 v26, v28, v28
	v_cndmask_b32_e64 v29, 0, 32, vcc
	v_ldexp_f32 v27, v27, v29
	v_log_f32_e32 v27, v27
	ds_read_u16 v29, v24 offset:12672
	ds_read_u16 v30, v24 offset:13200
	ds_read_u16 v31, v24 offset:13728
	ds_read_u16 v32, v24 offset:14256
	ds_read_u16 v33, v24 offset:14784
	ds_read_u16 v189, v24 offset:15312
	ds_read_u16 v190, v24 offset:15840
	ds_read_u16 v191, v24 offset:16368
	s_waitcnt lgkmcnt(0)
	v_lshlrev_b32_e32 v29, 16, v29
	v_mul_f32_e64 v24, |v29|, s19
	v_mul_f32_e32 v28, 0x3f317217, v27
	v_fma_f32 v28, v27, s97, -v28
	v_fmac_f32_e32 v28, 0x3377d1cf, v27
	v_exp_f32_e32 v192, v24
	v_fmac_f32_e32 v28, 0x3f317217, v27
	v_cmp_lt_f32_e64 s[38:39], |v27|, s15
	v_min_f32_e32 v26, 0, v26
	s_nop 0
	v_cndmask_b32_e64 v27, v27, v28, s[38:39]
	v_cndmask_b32_e32 v28, 0, v179, vcc
	v_sub_f32_e32 v24, v27, v28
	v_sub_f32_e32 v26, v26, v24
	v_fmamk_f32 v24, v25, 0x3d800000, v23
	v_add_f32_e32 v25, 1.0, v192
	v_cmp_gt_f32_e32 vcc, s96, v25
	s_nop 1
	v_cndmask_b32_e64 v27, 0, 32, vcc
	v_ldexp_f32 v25, v25, v27
	v_log_f32_e32 v27, v25
	v_fmamk_f32 v25, v26, 0x3d800000, v24
	v_max_f32_e32 v26, v29, v29
	v_lshlrev_b32_e32 v29, 16, v30
	v_mul_f32_e32 v28, 0x3f317217, v27
	v_mul_f32_e64 v30, |v29|, s19
	v_fma_f32 v28, v27, s97, -v28
	v_exp_f32_e32 v30, v30
	v_fmac_f32_e32 v28, 0x3377d1cf, v27
	v_fmac_f32_e32 v28, 0x3f317217, v27
	v_cmp_lt_f32_e64 s[38:39], |v27|, s15
	v_min_f32_e32 v26, 0, v26
	s_nop 0
	v_cndmask_b32_e64 v27, v27, v28, s[38:39]
	v_cndmask_b32_e32 v28, 0, v179, vcc
	v_sub_f32_e32 v27, v27, v28
	v_add_f32_e32 v28, 1.0, v30
	v_cmp_gt_f32_e32 vcc, s96, v28
	v_sub_f32_e32 v26, v26, v27
	v_max_f32_e32 v27, v29, v29
	v_cndmask_b32_e64 v30, 0, 32, vcc
	v_ldexp_f32 v28, v28, v30
	v_log_f32_e32 v28, v28
	v_lshlrev_b32_e32 v30, 16, v31
	v_mul_f32_e64 v31, |v30|, s19
	v_exp_f32_e32 v31, v31
	v_mul_f32_e32 v29, 0x3f317217, v28
	v_fma_f32 v29, v28, s97, -v29
	v_fmac_f32_e32 v29, 0x3377d1cf, v28
	v_fmac_f32_e32 v29, 0x3f317217, v28
	v_cmp_lt_f32_e64 s[38:39], |v28|, s15
	v_min_f32_e32 v27, 0, v27
	v_fmamk_f32 v26, v26, 0x3d800000, v25
	v_cndmask_b32_e64 v28, v28, v29, s[38:39]
	v_cndmask_b32_e32 v29, 0, v179, vcc
	v_sub_f32_e32 v28, v28, v29
	v_sub_f32_e32 v27, v27, v28
	v_add_f32_e32 v28, 1.0, v31
	v_cmp_gt_f32_e32 vcc, s96, v28
	v_lshlrev_b32_e32 v31, 16, v32
	v_mul_f32_e64 v32, |v31|, s19
	v_cndmask_b32_e64 v29, 0, 32, vcc
	v_ldexp_f32 v28, v28, v29
	v_log_f32_e32 v28, v28
	v_max_f32_e32 v29, v30, v30
	v_exp_f32_e32 v32, v32
	v_min_f32_e32 v29, 0, v29
	v_mul_f32_e32 v30, 0x3f317217, v28
	v_fma_f32 v30, v28, s97, -v30
	v_fmac_f32_e32 v30, 0x3377d1cf, v28
	v_fmac_f32_e32 v30, 0x3f317217, v28
	v_cmp_lt_f32_e64 s[38:39], |v28|, s15
	v_fmamk_f32 v27, v27, 0x3d800000, v26
	s_nop 0
	v_cndmask_b32_e64 v28, v28, v30, s[38:39]
	v_cndmask_b32_e32 v30, 0, v179, vcc
	v_sub_f32_e32 v28, v28, v30
	v_add_f32_e32 v30, 1.0, v32
	v_cmp_gt_f32_e32 vcc, s96, v30
	v_sub_f32_e32 v28, v29, v28
	v_max_f32_e32 v29, v31, v31
	v_cndmask_b32_e64 v32, 0, 32, vcc
	v_ldexp_f32 v30, v30, v32
	v_log_f32_e32 v30, v30
	v_lshlrev_b32_e32 v32, 16, v33
	v_mul_f32_e64 v33, |v32|, s19
	v_exp_f32_e32 v33, v33
	v_mul_f32_e32 v31, 0x3f317217, v30
	v_fma_f32 v31, v30, s97, -v31
	v_fmac_f32_e32 v31, 0x3377d1cf, v30
	v_fmac_f32_e32 v31, 0x3f317217, v30
	v_cmp_lt_f32_e64 s[38:39], |v30|, s15
	v_min_f32_e32 v29, 0, v29
	v_fmamk_f32 v28, v28, 0x3d800000, v27
	v_cndmask_b32_e64 v30, v30, v31, s[38:39]
	v_cndmask_b32_e32 v31, 0, v179, vcc
	v_sub_f32_e32 v30, v30, v31
	v_sub_f32_e32 v29, v29, v30
	v_add_f32_e32 v30, 1.0, v33
	v_cmp_gt_f32_e32 vcc, s96, v30
	v_lshlrev_b32_e32 v33, 16, v189
	v_mul_f32_e64 v189, |v33|, s19
	v_cndmask_b32_e64 v31, 0, 32, vcc
	v_ldexp_f32 v30, v30, v31
	v_log_f32_e32 v30, v30
	v_max_f32_e32 v31, v32, v32
	v_exp_f32_e32 v189, v189
	v_min_f32_e32 v31, 0, v31
	v_mul_f32_e32 v32, 0x3f317217, v30
	v_fma_f32 v32, v30, s97, -v32
	v_fmac_f32_e32 v32, 0x3377d1cf, v30
	v_fmac_f32_e32 v32, 0x3f317217, v30
	v_cmp_lt_f32_e64 s[38:39], |v30|, s15
	v_fmamk_f32 v29, v29, 0x3d800000, v28
	s_nop 0
	v_cndmask_b32_e64 v30, v30, v32, s[38:39]
	v_cndmask_b32_e32 v32, 0, v179, vcc
	v_sub_f32_e32 v30, v30, v32
	v_add_f32_e32 v32, 1.0, v189
	v_cmp_gt_f32_e32 vcc, s96, v32
	v_sub_f32_e32 v30, v31, v30
	v_max_f32_e32 v31, v33, v33
	v_cndmask_b32_e64 v189, 0, 32, vcc
	v_ldexp_f32 v32, v32, v189
	v_log_f32_e32 v32, v32
	v_lshlrev_b32_e32 v189, 16, v190
	v_mul_f32_e64 v190, |v189|, s19
	v_exp_f32_e32 v190, v190
	v_mul_f32_e32 v33, 0x3f317217, v32
	v_fma_f32 v33, v32, s97, -v33
	v_fmac_f32_e32 v33, 0x3377d1cf, v32
	v_fmac_f32_e32 v33, 0x3f317217, v32
	v_cmp_lt_f32_e64 s[38:39], |v32|, s15
	v_min_f32_e32 v31, 0, v31
	v_fmamk_f32 v30, v30, 0x3d800000, v29
	v_cndmask_b32_e64 v32, v32, v33, s[38:39]
	v_cndmask_b32_e32 v33, 0, v179, vcc
	v_sub_f32_e32 v32, v32, v33
	v_sub_f32_e32 v31, v31, v32
	v_add_f32_e32 v32, 1.0, v190
	v_cmp_gt_f32_e32 vcc, s96, v32
	v_lshlrev_b32_e32 v190, 16, v191
	v_mul_f32_e64 v191, |v190|, s19
	v_cndmask_b32_e64 v33, 0, 32, vcc
	v_ldexp_f32 v32, v32, v33
	v_log_f32_e32 v32, v32
	v_max_f32_e32 v33, v189, v189
	v_exp_f32_e32 v191, v191
	v_min_f32_e32 v33, 0, v33
	v_mul_f32_e32 v189, 0x3f317217, v32
	v_fma_f32 v189, v32, s97, -v189
	v_fmac_f32_e32 v189, 0x3377d1cf, v32
	v_fmac_f32_e32 v189, 0x3f317217, v32
	v_cmp_lt_f32_e64 s[38:39], |v32|, s15
	v_fmamk_f32 v31, v31, 0x3d800000, v30
	s_nop 0
	v_cndmask_b32_e64 v32, v32, v189, s[38:39]
	v_cndmask_b32_e32 v189, 0, v179, vcc
	v_sub_f32_e32 v32, v32, v189
	v_add_f32_e32 v189, 1.0, v191
	v_cmp_gt_f32_e32 vcc, s96, v189
	v_sub_f32_e32 v32, v33, v32
	v_max_f32_e32 v33, v190, v190
	v_cndmask_b32_e64 v191, 0, 32, vcc
	v_ldexp_f32 v189, v189, v191
	v_log_f32_e32 v189, v189
	v_min_f32_e32 v33, 0, v33
	v_fmamk_f32 v32, v32, 0x3d800000, v31
	v_mul_f32_e32 v190, 0x3f317217, v189
	v_fma_f32 v190, v189, s97, -v190
	v_fmac_f32_e32 v190, 0x3377d1cf, v189
	v_fmac_f32_e32 v190, 0x3f317217, v189
	v_cmp_lt_f32_e64 s[38:39], |v189|, s15
	s_nop 1
	v_cndmask_b32_e64 v189, v189, v190, s[38:39]
	v_cndmask_b32_e32 v190, 0, v179, vcc
	v_sub_f32_e32 v189, v189, v190
	v_sub_f32_e32 v33, v33, v189
	v_mov_b32_e32 v189, 2
	v_lshlrev_b32_e32 v190, 10, v160
	v_lshlrev_b32_sdwa v189, v189, v109 dst_sel:DWORD dst_unused:UNUSED_PAD src0_sel:DWORD src1_sel:BYTE_0
	v_fmamk_f32 v33, v33, 0x3d800000, v32
	v_add3_u32 v190, v187, v190, v189
	v_cmp_lt_u32_e32 vcc, s2, v109
	ds_write_b32 v190, v33
	s_waitcnt lgkmcnt(0)
	s_barrier
	s_and_saveexec_b64 s[2:3], vcc
	s_cbranch_execz .LBB0_168
	v_add_u32_e32 v187, v187, v189
	ds_read_b32 v190, v187
	s_waitcnt lgkmcnt(0)
	v_pk_add_f32 v[32:33], v[32:33], v[190:191] op_sel_hi:[1,0]
	v_pk_add_f32 v[30:31], v[30:31], v[190:191] op_sel_hi:[1,0]
	v_pk_add_f32 v[28:29], v[28:29], v[190:191] op_sel_hi:[1,0]
	v_pk_add_f32 v[26:27], v[26:27], v[190:191] op_sel_hi:[1,0]
	v_pk_add_f32 v[24:25], v[24:25], v[190:191] op_sel_hi:[1,0]
	v_pk_add_f32 v[22:23], v[22:23], v[190:191] op_sel_hi:[1,0]
	v_pk_add_f32 v[20:21], v[20:21], v[190:191] op_sel_hi:[1,0]
	v_pk_add_f32 v[18:19], v[18:19], v[190:191] op_sel_hi:[1,0]
	v_pk_add_f32 v[16:17], v[16:17], v[190:191] op_sel_hi:[1,0]
	v_pk_add_f32 v[14:15], v[14:15], v[190:191] op_sel_hi:[1,0]
	v_pk_add_f32 v[12:13], v[12:13], v[190:191] op_sel_hi:[1,0]
	v_pk_add_f32 v[10:11], v[10:11], v[190:191] op_sel_hi:[1,0]
	v_pk_add_f32 v[8:9], v[8:9], v[190:191] op_sel_hi:[1,0]
	v_pk_add_f32 v[6:7], v[6:7], v[190:191] op_sel_hi:[1,0]
	v_pk_add_f32 v[4:5], v[4:5], v[190:191] op_sel_hi:[1,0]
	v_pk_add_f32 v[2:3], v[2:3], v[190:191] op_sel_hi:[1,0]

.LBB0_173:
	s_and_b64 vcc, exec, s[2:3]
	s_cbranch_vccz .LBB0_253
	s_add_i32 s2, s85, 0xfffffe00
	s_lshr_b32 s2, s2, 7
	s_bfe_u32 s3, s85, 0x60001
	s_and_b32 s6, s85, 1
	s_lshl_b32 s7, s3, 7
	s_lshl_b32 s10, s2, 8
	s_lshl_b32 s3, s3, 2
	s_lshl_b32 s2, s2, 13
	s_lshl_b32 s54, s6, 1
	s_or_b32 s3, s3, s10
	s_or_b32 s52, s7, s2
	s_mov_b32 s2, 14
	s_or_b32 s38, s3, s54
	s_ashr_i32 s3, s2, 31
	s_lshl_b32 s53, s6, 7
	s_add_i32 s58, s52, -3
	s_sub_i32 s57, 0, s7
	s_lshl_b64 s[2:3], s[2:3], 3
	s_add_u32 s2, s0, s2
	s_mov_b32 s6, 15
	s_addc_u32 s3, s1, s3
	s_ashr_i32 s7, s6, 31
	s_lshl_b64 s[6:7], s[6:7], 3
	s_add_u32 s6, s0, s6
	s_mov_b32 s10, 16
	s_addc_u32 s7, s1, s7
	s_ashr_i32 s11, s10, 31
	s_lshl_b64 s[10:11], s[10:11], 3
	s_add_u32 s10, s0, s10
	s_mov_b32 s20, 17
	s_addc_u32 s11, s1, s11
	s_ashr_i32 s21, s20, 31
	s_lshl_b64 s[20:21], s[20:21], 3
	s_add_u32 s40, s0, s20
	s_mov_b32 s20, 18
	s_addc_u32 s41, s1, s21
	s_ashr_i32 s21, s20, 31
	s_lshl_b64 s[20:21], s[20:21], 3
	s_add_u32 s42, s0, s20
	s_mov_b32 s20, 19
	s_addc_u32 s43, s1, s21
	s_ashr_i32 s21, s20, 31
	s_lshl_b64 s[20:21], s[20:21], 3
	s_add_u32 s50, s0, s20
	v_mov_b32_e32 v104, v183
	v_readlane_b32 s20, v254, 53
	s_addc_u32 s51, s1, s21
	v_readfirstlane_b32 s55, v104
	s_bitcmp1_b32 s55, 8
	s_cselect_b32 s21, 0xc0, 0
	s_xor_b32 s55, s55, s21
	v_mov_b32_e32 v99, s20
	v_readlane_b32 s20, v254, 54
	s_ashr_i32 s56, s55, 8
	v_lshrrev_b32_e32 v0, 1, v104
	v_mov_b32_e32 v103, s20
	v_readlane_b32 s20, v254, 55
	v_and_b32_e32 v0, 16, v0
	v_and_b32_e32 v98, 63, v104
	v_mov_b32_e32 v101, s20
	s_add_i32 s20, s38, s56
	s_ashr_i32 s21, s20, 31
	s_lshl_b64 s[20:21], s[20:21], 14
	v_readlane_b32 s38, v254, 62
	v_readlane_b32 s39, v254, 63
	s_add_u32 s20, s38, s20
	s_addc_u32 s21, s39, s21
	v_lshl_add_u64 v[6:7], s[20:21], 0, v[0:1]
	v_lshlrev_b32_e32 v0, 8, v104
	v_and_b32_e32 v0, 0x1f00, v0
	v_lshl_add_u64 v[8:9], v[6:7], 0, v[0:1]
	v_mov_b32_e32 v0, 0x2000
	v_lshl_or_b32 v0, v98, 8, v0
	v_mov_b32_e32 v102, v1
	v_lshl_add_u64 v[6:7], v[6:7], 0, v[0:1]
	s_waitcnt lgkmcnt(0)
	s_barrier
	global_load_dwordx4 v[2:5], v[8:9], off
	global_load_dwordx4 v[78:81], v[8:9], off offset:32
	global_load_dwordx4 v[74:77], v[8:9], off offset:64
	global_load_dwordx4 v[66:69], v[8:9], off offset:96
	global_load_dwordx4 v[58:61], v[8:9], off offset:128
	global_load_dwordx4 v[54:57], v[8:9], off offset:160
	global_load_dwordx4 v[46:49], v[8:9], off offset:192
	global_load_dwordx4 v[38:41], v[8:9], off offset:224
	global_load_dwordx4 v[18:21], v[6:7], off
	global_load_dwordx4 v[86:89], v[6:7], off offset:32
	global_load_dwordx4 v[82:85], v[6:7], off offset:64
	global_load_dwordx4 v[70:73], v[6:7], off offset:96
	global_load_dwordx4 v[62:65], v[6:7], off offset:128
	global_load_dwordx4 v[50:53], v[6:7], off offset:160
	global_load_dwordx4 v[42:45], v[6:7], off offset:192
	global_load_dwordx4 v[34:37], v[6:7], off offset:224
	s_mov_b32 s20, 0x2aaaaaab
	v_mul_hi_i32 v0, v104, s20
	v_lshrrev_b32_e32 v6, 31, v0
	v_ashrrev_i32_e32 v0, 6, v0
	v_add_u32_e32 v25, v0, v6
	v_mul_i32_i24_e32 v0, 0x180, v25
	v_sub_u32_e32 v14, v104, v0
	v_lshlrev_b32_e32 v213, 1, v14
	v_and_b32_e32 v27, 0x7f, v14
	v_and_b32_e32 v0, 0xffffff00, v213
	v_lshlrev_b32_e32 v10, 5, v25
	v_or3_b32 v6, s53, v0, v27
	v_add_u32_e32 v0, s58, v10
	v_mov_b64_e32 v[8:9], s[26:27]
	v_mad_i64_i32 v[8:9], s[20:21], v0, s18, v[8:9]
	v_ashrrev_i32_e32 v7, 31, v6
	v_lshl_add_u64 v[6:7], v[6:7], 1, v[8:9]
	v_cmp_lt_i32_e64 s[38:39], s57, v10
	v_mov_b32_e32 v15, 0
	v_mov_b32_e32 v16, 0
	v_mov_b32_e32 v17, 0
	v_mov_b32_e32 v228, 0
	v_mov_b32_e32 v229, 0
	s_and_saveexec_b64 s[20:21], s[38:39]
	s_cbranch_execz .LBB0_176
	v_add_co_u32_e32 v8, vcc, 0x2000, v6
	s_nop 1
	v_addc_co_u32_e32 v9, vcc, 0, v7, vcc
	flat_load_ushort v228, v[8:9] offset:3584
	v_add_co_u32_e32 v8, vcc, 0x1000, v6
	s_nop 0
	s_nop 0
	v_addc_co_u32_e32 v9, vcc, 0, v7, vcc
	flat_load_ushort v229, v[8:9]
	s_nop 0
	s_nop 0
